# attention: static s_setprio 1 for waves 4-7; HGRN lf loads target live registers directly (16 moves per chunk removed)
# speedup vs baseline: 1.0094x; 1.0002x over previous
; template <bool SAFE>
; __device__ void phase_attn(const Params& p, const bf16_t* Qall, const bf16_t* Kall, const bf16_t* Vt, bf16_t* CAT, LAS unsigned char* lds) {
;   const int tid = threadIdx.x, w = __builtin_amdgcn_readfirstlane(tid >> 6), lane = tid & 63, r = lane & 31, hh = lane >> 5;
;   constexpr int KROW = 104, VROW = 72;
;   constexpr int KBYTES = 64 * KROW * 2, VBYTES = 64 * VROW * 2, BUF = KBYTES + VBYTES;
;   unsigned soff[3];
; #pragma unroll
;   for (int j = 0; j < 3; ++j) {
;     const int ci = (3 * w + j) * 64 + lane;
;     if (3 * w + j < 13) { const int row = ci / 13, part = ci % 13; soff[j] = (unsigned)(row * 96 + (part < 12 ? part : 0) * 8) * 2u; }
;     else { const int c2 = ci - 832, dv = c2 / 9, part = c2 % 9; soff[j] = (unsigned)((dv < 64 ? dv : 0) * NKEY + (part < 8 ? part : 0) * 8) * 2u; }
;   }
.LBB0_1233:
.LBB0_1234:
	v_readfirstlane_b32 s5, v176
	s_waitcnt lgkmcnt(0)
	s_lshr_b32 s4, s5, 6
	s_cmp_lt_u32 s4, 4
	s_cbranch_scc1 .Latt_prio_done
	s_setprio 1
.Latt_prio_done:
	v_and_b32_e32 v6, 63, v176
	s_mul_i32 s0, s4, 0xc0
	s_cmpk_lt_u32 s5, 0x140
	s_cselect_b64 s[10:11], -1, 0
	s_cmpk_gt_u32 s5, 0x13f
	v_or_b32_e32 v1, s0, v6
	s_cbranch_scc0 .LBB0_1236
	v_add_u32_e32 v0, 0xfffffcc0, v1
	s_mov_b32 s1, 0x38e38e39
	v_mul_hi_i32 v2, v0, s1
	v_lshrrev_b32_e32 v3, 31, v2
	v_ashrrev_i32_e32 v2, 1, v2
	v_add_u32_e32 v2, v2, v3
	v_lshl_add_u32 v3, v2, 3, v2
	s_cmpk_lt_u32 s0, 0x580
	s_movk_i32 s0, 0x2100
	v_sub_u32_e32 v0, v0, v3
	v_mul_lo_u32 v2, v2, s0
	s_cselect_b64 vcc, -1, 0
	v_cndmask_b32_e32 v2, 0, v2, vcc
	v_lshlrev_b32_e32 v3, 3, v0
	v_cmp_gt_i32_e32 vcc, 8, v0
	s_nop 1
	v_cndmask_b32_e32 v0, 0, v3, vcc
	v_add_u32_e32 v0, v2, v0
	s_cbranch_execz .LBB0_1237
	s_branch .LBB0_1238

; #define LAS __attribute__((address_space(3)))
; __device__ __forceinline__ unsigned xb_add(unsigned* p, unsigned v) { return __hip_atomic_fetch_add(p, v, __ATOMIC_RELAXED, __HIP_MEMORY_SCOPE_AGENT); }
; __device__ __forceinline__ unsigned xb_xcc_id() { return (unsigned)__builtin_amdgcn_s_getreg((3 << 11) | 20) & 0xFu; }
; __device__ __forceinline__ void xcd_barrier(unsigned* bar, volatile LAS unsigned* st) {
;   asm volatile("s_waitcnt vmcnt(0)" ::: "memory");
;   __syncthreads();
;   if (threadIdx.x == 0) {
;     const unsigned x = xb_xcc_id();
;     __builtin_amdgcn_s_waitcnt(0);
;     unsigned nloc = st[0], nx = st[1];
;     if (nloc == 0u) { xcd_barrier_complete(bar, x, nloc, nx); st[0] = nloc; st[1] = nx; }
;     const unsigned old = xb_add(&bar[XB_XSUB(x)], 1u);
;     const unsigned gen = old / nloc;
;     if (old + 1u == (gen + 1u) * nloc) {
; template <int PH>
; __device__ __forceinline__ void step(const Params& p, int ph0, int ph1, bf16_t* shm) {
;   if ((ph0 <= PH && PH < ph1) || (PH >= 24 && ph1 - ph0 > 1)) {
;     run_phase<PH>(p, shm);
;     if constexpr (PH == PROBE_DUP) { xcd_barrier(p.bar, (volatile LAS unsigned*)((LAS unsigned char*)shm + SHM_B)); run_phase<PH>(p, shm); }
;     if (PH != 23 && ph1 - ph0 > 1) xcd_barrier(p.bar, (volatile LAS unsigned*)((LAS unsigned char*)shm + SHM_B));
.LBB0_1268:
	s_setprio 0
	s_sub_i32 s22, s95, s94
	s_cmp_lt_i32 s22, 2
	s_mov_b32 s2, 1
	s_cbranch_scc1 .LBB0_1322
	s_waitcnt vmcnt(0)
	s_waitcnt vmcnt(0)
	s_barrier
	s_mov_b64 s[6:7], exec
	v_readlane_b32 s0, v244, 0
	v_readlane_b32 s1, v244, 1
	s_and_b64 s[0:1], s[6:7], s[0:1]
	s_mov_b64 exec, s[0:1]
	s_cbranch_execz .LBB0_1321
	s_add_i32 s1, 0, 0x20000
	v_mov_b32_e32 v0, s1
	s_getreg_b32 s0, hwreg(HW_REG_XCC_ID, 0, 4)
	s_waitcnt vmcnt(0) expcnt(0) lgkmcnt(0)
	ds_read_b32 v2, v0
	s_add_i32 s1, 0, 0x20004
	v_mov_b32_e32 v0, s1
	s_load_dwordx2 s[8:9], s[90:91], 0x140
	ds_read_b32 v0, v0
	s_waitcnt lgkmcnt(0)
	v_cmp_ne_u32_e32 vcc, 0, v2
	s_and_b32 s18, s0, 15
	s_cbranch_vccnz .LBB0_1285
	s_load_dwordx2 s[4:5], s[90:91], 0x168
	s_load_dword s3, s[90:91], 0x170
	s_add_u32 s0, s8, 0x1000
	s_addc_u32 s1, s9, 0
	s_add_u32 s2, s8, 0x1100
	s_waitcnt lgkmcnt(0)
	s_mul_i32 s19, s5, s4
	s_mul_i32 s19, s19, s3
	s_addc_u32 s3, s9, 0
	s_add_u32 s4, s8, 0x1200
	s_addc_u32 s5, s9, 0
	s_add_u32 s10, s8, 0x1300
	s_addc_u32 s11, s9, 0
	s_mov_b32 s20, 1
	v_mov_b32_e32 v16, 0
	s_branch .LBB0_1273

; #define LAS __attribute__((address_space(3)))
; template <bool OUT>
; __device__ void phase_hgrn(const Params& p, const bf16_t* Qh, const bf16_t* Vv, const _Float16* Lfb, bf16_t* Of, bf16_t* Ob, float* Sseg, float* Dlog, LAS unsigned char* lds) {
;     ...
;     for (int c = c_begin; c < c_end; ++c) {
;       const int rbase = (c < 4) ? b * 256 + (dir ? 255 - 64 * c : 64 * c) : NCTX + b * 8192 + (dir ? 8191 - 64 * (c - 4) : 64 * (c - 4));
;       float lf[16], cs[16];
;       float run = 0.f;
; #pragma unroll
;       for (int i = 0; i < 16; ++i) { lf[i] = (float)lfr[i]; run += lf[i]; cs[i] = run; }
;       *(LAS float*)(lds + TOT + (tq * 128 + dk) * 4) = run;
;       __syncthreads();
;       float offs = 0.f, blast = 0.f;
; #pragma unroll
;       for (int g = 0; g < 4; ++g) { const float t = *(const LAS float*)(lds + TOT + (g * 128 + dk) * 4); blast += t; if (g < tq) offs += t; }
;       {
;         const float eblast = __expf(blast);
;         unsigned kew[8], vw[8];
; #pragma unroll
;         for (int i = 0; i < 16; i += 2) {
;           float qt[2], kt[2], ke[2];
; #pragma unroll
;           for (int e = 0; e < 2; ++e) {
;             const float bb = offs + cs[i + e];
;             const float k = 1.f - __expf(lf[i + e]);
;             const float ken = k * __expf(-bb);
;             if constexpr (OUT) { qt[e] = bf2f(qr[i + e]) * __expf(bb); kt[e] = ken; }
;             ke[e] = ken * eblast;
;           }
;           if constexpr (OUT) {
;             const unsigned qp = pk2(qt[0], qt[1]), kp = pk2(kt[0], kt[1]);
;             const int s = 16 * tq + i;
;             *(LAS bf16_t*)(lds + QT + (s * 136 + dk) * 2) = (bf16_t)(qp & 0xffffu);
;             *(LAS bf16_t*)(lds + QT + ((s + 1) * 136 + dk) * 2) = (bf16_t)(qp >> 16);
;             *(LAS bf16_t*)(lds + KT + (s * 136 + dk) * 2) = (bf16_t)(kp & 0xffffu);
;             *(LAS bf16_t*)(lds + KT + ((s + 1) * 136 + dk) * 2) = (bf16_t)(kp >> 16);
;           }
;           kew[i >> 1] = pk2(ke[0], ke[1]);
;           vw[i >> 1] = (unsigned)vr[i] | ((unsigned)vr[i + 1] << 16);
;         }
;         *(LAS u32x4*)(lds + KE + (dk * 72 + 16 * tq) * 2) = (u32x4){kew[0], kew[1], kew[2], kew[3]};
;         *(LAS u32x4*)(lds + KE + (dk * 72 + 16 * tq + 8) * 2) = (u32x4){kew[4], kew[5], kew[6], kew[7]};
;         *(LAS u32x4*)(lds + VT + (dk * 72 + 16 * tq) * 2) = (u32x4){vw[0], vw[1], vw[2], vw[3]};
.Lhga_keep:
	v_add_u32_e32 v228, s98, v61
	v_ashrrev_i32_e32 v229, 31, v228
	v_lshlrev_b64 v[228:229], 11, v[228:229]
	v_lshl_or_b32 v228, v52, 1, v228
	v_cvt_f32_f16_e32 v54, v62
	v_cvt_f32_f16_e32 v83, v63
	v_cvt_f32_f16_e32 v84, v64
	v_cvt_f32_f16_e32 v85, v65
	v_add_f32_e32 v82, 0, v54
	v_cvt_f32_f16_e32 v89, v66
	v_add_f32_e32 v86, v82, v83
	v_cvt_f32_f16_e32 v90, v67
	v_add_f32_e32 v87, v86, v84
	v_cvt_f32_f16_e32 v91, v68
	v_add_f32_e32 v88, v87, v85
	v_cvt_f32_f16_e32 v92, v69
	v_add_f32_e32 v93, v88, v89
	v_cvt_f32_f16_e32 v97, v70
	v_add_f32_e32 v94, v93, v90
	v_cvt_f32_f16_e32 v98, v71
	v_add_f32_e32 v95, v94, v91
	v_cvt_f32_f16_e32 v99, v72
	v_add_f32_e32 v96, v95, v92
	v_cvt_f32_f16_e32 v100, v73
	v_add_f32_e32 v101, v96, v97
	v_cvt_f32_f16_e32 v105, v74
	v_add_f32_e32 v102, v101, v98
	v_cvt_f32_f16_e32 v106, v75
	v_add_f32_e32 v103, v102, v99
	v_cvt_f32_f16_e32 v107, v76
	v_add_f32_e32 v104, v103, v100
	s_waitcnt vmcnt(0)
	v_cvt_f32_f16_e32 v108, v77
	v_add_f32_e32 v109, v104, v105
	v_add_f32_e32 v110, v109, v106
	v_add_f32_e32 v111, v110, v107
	v_add_f32_e32 v112, v111, v108
	v_add_u32_e32 v80, s60, v44
	ds_write_b32 v59, v112
	s_waitcnt lgkmcnt(0)
	s_barrier
	ds_read2st64_b32 v[78:79], v80 offset1:2
	ds_read2st64_b32 v[80:81], v80 offset0:4 offset1:6
	v_mul_f32_e32 v54, 0x3fb8aa3b, v54
	s_waitcnt lgkmcnt(1)
	v_add_f32_e32 v78, 0, v78
	v_cndmask_b32_e64 v113, v78, 0, s[6:7]
	global_load_ushort v62, v228, s[20:21]
	v_add_f32_e32 v78, v78, v79
	v_add_f32_e32 v79, v79, v113
	v_cndmask_b32_e64 v79, v113, v79, s[8:9]
	s_waitcnt lgkmcnt(0)
	global_load_ushort v212, v228, s[14:15]
	v_add_u32_e32 v230, s22, v228
	v_add_f32_e32 v78, v78, v80
	v_add_f32_e32 v80, v80, v79
	v_cndmask_b32_e64 v79, v79, v80, s[10:11]
	v_add_f32_e32 v80, v81, v79
	global_load_ushort v63, v230, s[20:21]
	v_cndmask_b32_e64 v79, v79, v80, s[12:13]
	v_add_f32_e32 v78, v78, v81
	v_add_f32_e32 v81, v82, v79
	v_exp_f32_e32 v80, v54
	global_load_ushort v213, v230, s[14:15]
	v_add_u32_e32 v231, s24, v228
	v_mul_f32_e32 v54, 0xbfb8aa3b, v81
	v_exp_f32_e32 v82, v54
	v_add_f32_e32 v54, v86, v79
	v_mul_f32_e32 v81, 0x3fb8aa3b, v83
	global_load_ushort v64, v231, s[20:21]
	v_exp_f32_e32 v81, v81
	v_mul_f32_e32 v54, 0xbfb8aa3b, v54
	v_exp_f32_e32 v83, v54
	v_mul_f32_e32 v54, 0x3fb8aa3b, v78
	global_load_ushort v214, v231, s[14:15]
	v_add_u32_e32 v232, s26, v228
	v_pk_add_f32 v[80:81], v[80:81], 1.0 op_sel_hi:[1,0] neg_lo:[1,0] neg_hi:[1,0]
	v_exp_f32_e32 v54, v54
	v_pk_mul_f32 v[80:81], v[80:81], v[82:83]
	v_add_f32_e32 v83, v87, v79
	global_load_ushort v65, v232, s[20:21]
	v_mul_f32_e32 v83, 0xbfb8aa3b, v83
	v_mul_f32_e32 v82, 0x3fb8aa3b, v84
	v_exp_f32_e32 v84, v83
	v_add_f32_e32 v86, v88, v79
	global_load_ushort v215, v232, s[14:15]
	v_add_u32_e32 v233, s28, v228
	v_mul_f32_e32 v83, 0x3fb8aa3b, v85
	v_exp_f32_e32 v82, v82
	v_exp_f32_e32 v83, v83
	v_mul_f32_e32 v85, 0xbfb8aa3b, v86
	global_load_ushort v66, v233, s[20:21]
	v_exp_f32_e32 v85, v85
	v_pk_mul_f32 v[80:81], v[54:55], v[80:81] op_sel_hi:[0,1]
	v_cvt_pk_bf16_f32 v80, v80, v81
	v_pk_add_f32 v[82:83], v[82:83], 1.0 op_sel_hi:[1,0] neg_lo:[1,0] neg_hi:[1,0]
	global_load_ushort v216, v233, s[14:15]
	v_add_u32_e32 v234, s30, v228
	v_add_f32_e32 v81, v93, v79
	v_pk_mul_f32 v[82:83], v[82:83], v[84:85]
	v_mul_f32_e32 v84, 0x3fb8aa3b, v89
	global_load_ushort v67, v234, s[20:21]
	v_mul_f32_e32 v81, 0xbfb8aa3b, v81
	v_mul_f32_e32 v85, 0x3fb8aa3b, v90
	v_exp_f32_e32 v84, v84
	v_exp_f32_e32 v86, v81
	global_load_ushort v217, v234, s[14:15]
	v_add_u32_e32 v235, s34, v228
	v_add_f32_e32 v81, v94, v79
	v_exp_f32_e32 v85, v85
	v_mul_f32_e32 v81, 0xbfb8aa3b, v81
	v_exp_f32_e32 v87, v81
	global_load_ushort v68, v235, s[20:21]
	v_pk_mul_f32 v[82:83], v[54:55], v[82:83] op_sel_hi:[0,1]
	v_cvt_pk_bf16_f32 v81, v82, v83
	v_pk_add_f32 v[82:83], v[84:85], 1.0 op_sel_hi:[1,0] neg_lo:[1,0] neg_hi:[1,0]
	v_add_f32_e32 v85, v95, v79
	global_load_ushort v218, v235, s[14:15]
	v_add_u32_e32 v236, s36, v228
	v_mul_f32_e32 v85, 0xbfb8aa3b, v85
	v_pk_mul_f32 v[82:83], v[82:83], v[86:87]
	v_mul_f32_e32 v84, 0x3fb8aa3b, v91
	v_exp_f32_e32 v86, v85
	global_load_ushort v69, v236, s[20:21]
	v_add_f32_e32 v87, v96, v79
	v_mul_f32_e32 v85, 0x3fb8aa3b, v92
	v_exp_f32_e32 v84, v84
	v_exp_f32_e32 v85, v85
	global_load_ushort v219, v236, s[14:15]
	v_add_u32_e32 v237, s38, v228
	v_mul_f32_e32 v87, 0xbfb8aa3b, v87
	v_exp_f32_e32 v87, v87
	v_pk_mul_f32 v[82:83], v[54:55], v[82:83] op_sel_hi:[0,1]
	v_cvt_pk_bf16_f32 v82, v82, v83
	global_load_ushort v70, v237, s[20:21]
	v_pk_add_f32 v[84:85], v[84:85], 1.0 op_sel_hi:[1,0] neg_lo:[1,0] neg_hi:[1,0]
	v_add_f32_e32 v83, v101, v79
	v_pk_mul_f32 v[84:85], v[84:85], v[86:87]
	v_mul_f32_e32 v86, 0x3fb8aa3b, v97
	global_load_ushort v220, v237, s[14:15]
	v_add_u32_e32 v230, s40, v228
	v_mul_f32_e32 v83, 0xbfb8aa3b, v83
	v_mul_f32_e32 v87, 0x3fb8aa3b, v98
	v_exp_f32_e32 v86, v86
	v_exp_f32_e32 v88, v83
	global_load_ushort v71, v230, s[20:21]
	v_add_f32_e32 v83, v102, v79
	v_exp_f32_e32 v87, v87
	v_mul_f32_e32 v83, 0xbfb8aa3b, v83
	v_exp_f32_e32 v89, v83
	global_load_ushort v221, v230, s[14:15]
	v_add_u32_e32 v231, s42, v228
	v_pk_mul_f32 v[84:85], v[54:55], v[84:85] op_sel_hi:[0,1]
	v_cvt_pk_bf16_f32 v83, v84, v85
	v_pk_add_f32 v[84:85], v[86:87], 1.0 op_sel_hi:[1,0] neg_lo:[1,0] neg_hi:[1,0]
	v_add_f32_e32 v87, v103, v79
	global_load_ushort v72, v231, s[20:21]
; template <bool OUT>
; __device__ void phase_hgrn(const Params& p, const bf16_t* Qh, const bf16_t* Vv, const _Float16* Lfb, bf16_t* Of, bf16_t* Ob, float* Sseg, float* Dlog, LAS unsigned char* lds) {
;     ...
;           kew[i >> 1] = pk2(ke[0], ke[1]);
;           vw[i >> 1] = (unsigned)vr[i] | ((unsigned)vr[i + 1] << 16);
;         }
;         *(LAS u32x4*)(lds + KE + (dk * 72 + 16 * tq) * 2) = (u32x4){kew[0], kew[1], kew[2], kew[3]};
;         *(LAS u32x4*)(lds + KE + (dk * 72 + 16 * tq + 8) * 2) = (u32x4){kew[4], kew[5], kew[6], kew[7]};
;         *(LAS u32x4*)(lds + VT + (dk * 72 + 16 * tq) * 2) = (u32x4){vw[0], vw[1], vw[2], vw[3]};
;         *(LAS u32x4*)(lds + VT + (dk * 72 + 16 * tq + 8) * 2) = (u32x4){vw[4], vw[5], vw[6], vw[7]};
;         if (tq == 0) *(LAS float*)(lds + DC + dk * 4) = eblast;
;         dsum += blast;
;       }
;       __syncthreads();
;       if (c + 1 < c_end) {
;         const int cn = c + 1;
;         const int rb = (cn < 4) ? b * 256 + (dir ? 255 - 64 * cn : 64 * cn) : NCTX + b * 8192 + (dir ? 8191 - 64 * (cn - 4) : 64 * (cn - 4));
;         const size_t o0 = (size_t)(rb + sgn * 16 * tq) * DM + h * 128 + dk;
; #pragma unroll
;         for (int i = 0; i < 16; ++i) { const size_t o = o0 + (ptrdiff_t)(sgn * i) * DM; lfr[i] = Lx[o]; if constexpr (OUT) qr[i] = Qh[o]; else qr[i] = 0; vr[i] = Vv[o]; }
;       }
;       if (OUT && w < 3) {
;         const int sb = (w == 2) ? 1 : 0, tb = (w == 0) ? 0 : 1;
;         f32x16 a;
; #pragma unroll
;         for (int e = 0; e < 16; ++e) a[e] = 0.f;
; #pragma unroll
;         for (int ks = 0; ks < 8; ++ks) {
;           const bf16x8 ka = *(const LAS bf16x8*)(lds + KT + ((32 * sb + r) * 136 + 16 * ks + 8 * hh) * 2);
;           const bf16x8 qb = *(const LAS bf16x8*)(lds + QT + ((32 * tb + r) * 136 + 16 * ks + 8 * hh) * 2);
;           a = __builtin_amdgcn_mfma_f32_32x32x16_bf16(ka, qb, a, 0, 0, 0);
;         }
;         const int tok = 32 * tb + r;
; #pragma unroll
;         for (int g = 0; g < 4; ++g) {
;           const int s0 = 32 * sb + 8 * g + 4 * hh;
;           const float v0 = (s0 + 0 <= tok) ? a[4 * g + 0] : 0.f, v1 = (s0 + 1 <= tok) ? a[4 * g + 1] : 0.f;
;           const float v2 = (s0 + 2 <= tok) ? a[4 * g + 2] : 0.f, v3 = (s0 + 3 <= tok) ? a[4 * g + 3] : 0.f;
;           u32x2 o; o.x = pk2(v0, v1); o.y = pk2(v2, v3);
;           *(LAS u32x2*)(lds + AT + (tok * 72 + s0) * 2) = o;
	v_mul_f32_e32 v87, 0xbfb8aa3b, v87
	v_pk_mul_f32 v[84:85], v[84:85], v[88:89]
	v_mul_f32_e32 v86, 0x3fb8aa3b, v99
	global_load_ushort v222, v231, s[14:15]
	v_add_u32_e32 v232, s44, v228
	v_exp_f32_e32 v88, v87
	v_add_f32_e32 v89, v104, v79
	v_mul_f32_e32 v87, 0x3fb8aa3b, v100
	v_exp_f32_e32 v86, v86
	global_load_ushort v73, v232, s[20:21]
	v_exp_f32_e32 v87, v87
	v_mul_f32_e32 v89, 0xbfb8aa3b, v89
	v_exp_f32_e32 v89, v89
	v_pk_mul_f32 v[84:85], v[54:55], v[84:85] op_sel_hi:[0,1]
	global_load_ushort v223, v232, s[14:15]
	v_add_u32_e32 v233, s46, v228
	v_cvt_pk_bf16_f32 v84, v84, v85
	v_pk_add_f32 v[86:87], v[86:87], 1.0 op_sel_hi:[1,0] neg_lo:[1,0] neg_hi:[1,0]
	v_add_f32_e32 v85, v109, v79
	v_pk_mul_f32 v[86:87], v[86:87], v[88:89]
	global_load_ushort v74, v233, s[20:21]
	v_mul_f32_e32 v88, 0x3fb8aa3b, v105
	v_mul_f32_e32 v85, 0xbfb8aa3b, v85
	v_mul_f32_e32 v89, 0x3fb8aa3b, v106
	v_exp_f32_e32 v88, v88
	global_load_ushort v224, v233, s[14:15]
	v_add_u32_e32 v234, s48, v228
	v_exp_f32_e32 v90, v85
	v_add_f32_e32 v85, v110, v79
	v_exp_f32_e32 v89, v89
	v_mul_f32_e32 v85, 0xbfb8aa3b, v85
	global_load_ushort v75, v234, s[20:21]
	v_exp_f32_e32 v91, v85
	v_pk_mul_f32 v[86:87], v[54:55], v[86:87] op_sel_hi:[0,1]
	v_cvt_pk_bf16_f32 v85, v86, v87
	v_pk_add_f32 v[86:87], v[88:89], 1.0 op_sel_hi:[1,0] neg_lo:[1,0] neg_hi:[1,0]
	global_load_ushort v225, v234, s[14:15]
	v_add_u32_e32 v235, s50, v228
	v_add_f32_e32 v89, v111, v79
	v_mul_f32_e32 v89, 0xbfb8aa3b, v89
	v_pk_mul_f32 v[86:87], v[86:87], v[90:91]
	v_mul_f32_e32 v88, 0x3fb8aa3b, v107
	global_load_ushort v76, v235, s[20:21]
	v_exp_f32_e32 v90, v89
	v_add_f32_e32 v79, v112, v79
	v_mul_f32_e32 v89, 0x3fb8aa3b, v108
	v_exp_f32_e32 v88, v88
	global_load_ushort v226, v235, s[14:15]
	v_add_u32_e32 v236, s52, v228
	v_exp_f32_e32 v89, v89
	v_mul_f32_e32 v79, 0xbfb8aa3b, v79
	v_exp_f32_e32 v91, v79
	v_pk_mul_f32 v[86:87], v[54:55], v[86:87] op_sel_hi:[0,1]
	global_load_ushort v77, v236, s[20:21]
	v_pk_add_f32 v[88:89], v[88:89], 1.0 op_sel_hi:[1,0] neg_lo:[1,0] neg_hi:[1,0]
	v_cvt_pk_bf16_f32 v86, v86, v87
	v_pk_mul_f32 v[88:89], v[88:89], v[90:91]
	s_nop 0
	global_load_ushort v227, v236, s[14:15]
	v_pk_mul_f32 v[88:89], v[54:55], v[88:89] op_sel_hi:[0,1]
	v_cvt_pk_bf16_f32 v87, v88, v89
	ds_write_b128 v55, v[80:83] offset:34816
	ds_write_b128 v55, v[84:87] offset:34832
	ds_write_b128 v55, v[32:35] offset:53248
	ds_write_b128 v55, v[36:39] offset:53264
	s_and_saveexec_b64 s[0:1], s[6:7]
	v_add_u32_e32 v79, 0, v53
	v_add_u32_e32 v79, 0x1c400, v79
	ds_write_b32 v79, v54
	s_or_b64 exec, exec, s[0:1]
	s_add_i32 s4, s63, 1
	s_cmp_ge_i32 s4, s62
	s_waitcnt lgkmcnt(0)
	s_barrier
.LBB0_2217:
	ds_read_b128 v[80:83], v56
	ds_read_b128 v[84:87], v56 offset:32
	ds_read_b128 v[88:91], v56 offset:64
	ds_read_b128 v[92:95], v56 offset:96
	ds_read_b128 v[96:99], v56 offset:128
	ds_read_b128 v[100:103], v56 offset:160
	ds_read_b128 v[104:107], v56 offset:192
	ds_read_b128 v[108:111], v56 offset:224
	v_add_u32_e32 v54, 0, v45
	s_waitcnt lgkmcnt(5)
	v_pk_mul_f32 v[8:9], v[8:9], v[88:89]
	v_pk_mul_f32 v[10:11], v[10:11], v[90:91]
	ds_read_b128 v[88:91], v54 offset:34816
	v_pk_mul_f32 v[0:1], v[0:1], v[80:81]
	v_pk_mul_f32 v[2:3], v[2:3], v[82:83]
	ds_read_b128 v[80:83], v57 offset:53248
	s_waitcnt lgkmcnt(6)
	v_pk_mul_f32 v[12:13], v[12:13], v[92:93]
	v_pk_mul_f32 v[4:5], v[4:5], v[84:85]
	v_pk_mul_f32 v[14:15], v[14:15], v[94:95]
	v_pk_mul_f32 v[6:7], v[6:7], v[86:87]
	ds_read_b128 v[84:87], v57 offset:53280
	ds_read_b128 v[92:95], v54 offset:34848
	ds_read_b128 v[112:115], v58 offset:34816
	s_waitcnt lgkmcnt(3)
	v_mfma_f32_32x32x16_bf16 v[0:15], v[88:91], v[80:83], v[0:15]
	v_mul_f32_e64 v28, v28, v108
	v_mul_f32_e64 v29, v29, v109
	v_mul_f32_e64 v24, v24, v104
	v_mul_f32_e64 v25, v25, v105
	v_mul_f32_e64 v20, v20, v100
	v_mul_f32_e64 v21, v21, v101
	v_pk_mul_f32 v[16:17], v[16:17], v[96:97]
	v_pk_mul_f32 v[30:31], v[30:31], v[110:111]
	v_pk_mul_f32 v[26:27], v[26:27], v[106:107]
	v_pk_mul_f32 v[22:23], v[22:23], v[102:103]
	v_pk_mul_f32 v[18:19], v[18:19], v[98:99]
	ds_read_b128 v[88:91], v58 offset:34848
	s_waitcnt lgkmcnt(2)
	v_mfma_f32_32x32x16_bf16 v[0:15], v[92:95], v[84:87], v[0:15]
	s_add_i32 s54, s54, 64
	s_sub_i32 s3, s3, 64
	v_add_f32_e32 v60, v60, v78
	s_cmpk_eq_i32 s54, 0x840
	s_waitcnt lgkmcnt(1)
	v_mfma_f32_32x32x16_bf16 v[16:31], v[112:115], v[80:83], v[16:31]
	s_waitcnt lgkmcnt(0)
	v_mfma_f32_32x32x16_bf16 v[16:31], v[88:91], v[84:87], v[16:31]
	ds_read_b128 v[80:83], v54 offset:34880
	ds_read_b128 v[84:87], v57 offset:53312
	ds_read_b128 v[88:91], v57 offset:53344
	ds_read_b128 v[92:95], v54 offset:34912
	s_waitcnt lgkmcnt(2)
	v_mfma_f32_32x32x16_bf16 v[0:15], v[80:83], v[84:87], v[0:15]
	ds_read_b128 v[80:83], v58 offset:34880
	ds_read_b128 v[96:99], v58 offset:34912
	s_waitcnt lgkmcnt(1)
	v_mfma_f32_32x32x16_bf16 v[16:31], v[80:83], v[84:87], v[16:31]
	v_mfma_f32_32x32x16_bf16 v[0:15], v[92:95], v[88:91], v[0:15]
	s_waitcnt lgkmcnt(0)
	v_mfma_f32_32x32x16_bf16 v[16:31], v[96:99], v[88:91], v[16:31]
	s_cbranch_scc1 .LBB0_2219
	s_waitcnt vmcnt(0)
	v_lshl_or_b32 v32, v213, 16, v212
	v_lshl_or_b32 v33, v215, 16, v214
	v_lshl_or_b32 v34, v217, 16, v216
	v_lshl_or_b32 v35, v219, 16, v218
	v_lshl_or_b32 v36, v221, 16, v220
	v_lshl_or_b32 v37, v223, 16, v222
	v_lshl_or_b32 v38, v225, 16, v224
	v_lshl_or_b32 v39, v227, 16, v226
	s_mov_b32 s63, s4
	s_branch .LBB0_2209

; #define LAS __attribute__((address_space(3)))
; template <bool OUT>
; __device__ void phase_hgrn(const Params& p, const bf16_t* Qh, const bf16_t* Vv, const _Float16* Lfb, bf16_t* Of, bf16_t* Ob, float* Sseg, float* Dlog, LAS unsigned char* lds) {
;     ...
;     for (int c = c_begin; c < c_end; ++c) {
;       const int rbase = (c < 4) ? b * 256 + (dir ? 255 - 64 * c : 64 * c) : NCTX + b * 8192 + (dir ? 8191 - 64 * (c - 4) : 64 * (c - 4));
;       float lf[16], cs[16];
;       float run = 0.f;
; #pragma unroll
;       for (int i = 0; i < 16; ++i) { lf[i] = (float)lfr[i]; run += lf[i]; cs[i] = run; }
;       *(LAS float*)(lds + TOT + (tq * 128 + dk) * 4) = run;
;       __syncthreads();
;       float offs = 0.f, blast = 0.f;
; #pragma unroll
;       for (int g = 0; g < 4; ++g) { const float t = *(const LAS float*)(lds + TOT + (g * 128 + dk) * 4); blast += t; if (g < tq) offs += t; }
;       {
;         const float eblast = __expf(blast);
;         unsigned kew[8], vw[8];
; #pragma unroll
;         for (int i = 0; i < 16; i += 2) {
;           float qt[2], kt[2], ke[2];
; #pragma unroll
;           for (int e = 0; e < 2; ++e) {
;             const float bb = offs + cs[i + e];
;             const float k = 1.f - __expf(lf[i + e]);
;             const float ken = k * __expf(-bb);
;             if constexpr (OUT) { qt[e] = bf2f(qr[i + e]) * __expf(bb); kt[e] = ken; }
;             ke[e] = ken * eblast;
;           }
;           if constexpr (OUT) {
;             const unsigned qp = pk2(qt[0], qt[1]), kp = pk2(kt[0], kt[1]);
;             const int s = 16 * tq + i;
;             *(LAS bf16_t*)(lds + QT + (s * 136 + dk) * 2) = (bf16_t)(qp & 0xffffu);
;             *(LAS bf16_t*)(lds + QT + ((s + 1) * 136 + dk) * 2) = (bf16_t)(qp >> 16);
;             *(LAS bf16_t*)(lds + KT + (s * 136 + dk) * 2) = (bf16_t)(kp & 0xffffu);
;             *(LAS bf16_t*)(lds + KT + ((s + 1) * 136 + dk) * 2) = (bf16_t)(kp >> 16);
;           }
;           kew[i >> 1] = pk2(ke[0], ke[1]);
;           vw[i >> 1] = (unsigned)vr[i] | ((unsigned)vr[i + 1] << 16);
;         }
;         *(LAS u32x4*)(lds + KE + (dk * 72 + 16 * tq) * 2) = (u32x4){kew[0], kew[1], kew[2], kew[3]};
;         *(LAS u32x4*)(lds + KE + (dk * 72 + 16 * tq + 8) * 2) = (u32x4){kew[4], kew[5], kew[6], kew[7]};
;         *(LAS u32x4*)(lds + VT + (dk * 72 + 16 * tq) * 2) = (u32x4){vw[0], vw[1], vw[2], vw[3]};
.LBB0_2292:
	v_cvt_f32_f16_e32 v37, v118
	v_cvt_f32_f16_e32 v39, v119
	v_cvt_f32_f16_e32 v40, v120
	v_cvt_f32_f16_e32 v41, v121
	v_add_f32_e32 v38, 0, v37
	v_cvt_f32_f16_e32 v45, v122
	v_add_f32_e32 v42, v38, v39
	v_cvt_f32_f16_e32 v46, v123
	v_add_f32_e32 v43, v42, v40
	v_cvt_f32_f16_e32 v47, v115
	v_add_f32_e32 v44, v43, v41
	v_cvt_f32_f16_e32 v56, v116
	v_add_f32_e32 v57, v44, v45
	v_cvt_f32_f16_e32 v61, v125
	v_add_f32_e32 v58, v57, v46
	v_cvt_f32_f16_e32 v62, v126
	v_add_f32_e32 v59, v58, v47
	v_cvt_f32_f16_e32 v63, v127
	v_add_f32_e32 v60, v59, v56
	v_cvt_f32_f16_e32 v140, v130
	v_add_f32_e32 v141, v60, v61
	v_cvt_f32_f16_e32 v145, v131
	v_add_f32_e32 v142, v141, v62
	v_cvt_f32_f16_e32 v146, v132
	v_add_f32_e32 v143, v142, v63
	v_cvt_f32_f16_e32 v147, v128
	v_add_f32_e32 v144, v143, v140
	v_cvt_f32_f16_e32 v148, v129
	v_add_f32_e32 v149, v144, v145
	v_add_f32_e32 v150, v149, v146
	v_add_f32_e32 v151, v150, v147
	v_add_f32_e32 v152, v151, v148
	v_add_u32_e32 v32, s25, v79
	ds_write_b32 v32, v152
	s_waitcnt lgkmcnt(0)
	s_barrier
	ds_read2st64_b32 v[32:33], v84 offset1:2
	ds_read2st64_b32 v[34:35], v84 offset0:4 offset1:6
	s_waitcnt lgkmcnt(1)
	v_add_f32_e32 v32, 0, v32
	v_cndmask_b32_e64 v36, v32, 0, s[6:7]
	v_add_f32_e32 v32, v32, v33
	v_add_f32_e32 v33, v33, v36
	v_cndmask_b32_e64 v33, v36, v33, s[10:11]
	s_waitcnt lgkmcnt(0)
	v_add_f32_e32 v32, v32, v34
	v_add_f32_e32 v34, v34, v33
	v_cndmask_b32_e64 v33, v33, v34, s[12:13]
	v_add_f32_e32 v34, v35, v33
	global_load_ushort v118, v228, s[64:65]
	v_cndmask_b32_e64 v153, v33, v34, s[14:15]
	v_add_f32_e32 v32, v32, v35
	v_add_f32_e32 v33, v38, v153
	v_mul_f32_e32 v32, 0x3fb8aa3b, v32
	v_mul_f32_e32 v34, 0xbfb8aa3b, v33
	global_load_ushort v196, v228, s[54:55]
	v_mul_f32_e32 v33, 0x3fb8aa3b, v33
	v_exp_f32_e32 v36, v32
	v_mul_f32_e32 v32, 0x3fb8aa3b, v37
	v_exp_f32_e32 v38, v33
	v_mul_f32_e32 v33, 0x3fb8aa3b, v39
	global_load_ushort v212, v228, s[60:61]
	v_add_u32_e32 v230, s66, v228
	v_add_f32_e32 v37, v42, v153
	v_exp_f32_e32 v32, v32
	v_exp_f32_e32 v33, v33
	v_mul_f32_e32 v35, 0xbfb8aa3b, v37
	v_exp_f32_e32 v34, v34
	global_load_ushort v119, v230, s[64:65]
	v_exp_f32_e32 v35, v35
	v_mul_f32_e32 v37, 0x3fb8aa3b, v37
	v_exp_f32_e32 v39, v37
	v_pk_add_f32 v[32:33], v[32:33], 1.0 op_sel_hi:[1,0] neg_lo:[1,0] neg_hi:[1,0]
	global_load_ushort v197, v230, s[54:55]
	s_nop 0
	v_pk_mul_f32 v[32:33], v[32:33], v[34:35]
	v_and_b32_e32 v35, 0xffff0000, v75
	v_lshlrev_b32_e32 v34, 16, v75
	v_pk_mul_f32 v[34:35], v[38:39], v[34:35]
	global_load_ushort v213, v230, s[60:61]
	v_add_u32_e32 v231, s68, v228
	v_pk_mul_f32 v[38:39], v[36:37], v[32:33] op_sel_hi:[0,1]
	v_cvt_pk_bf16_f32 v32, v32, v33
	v_add_f32_e32 v33, v43, v153
	v_cvt_pk_bf16_f32 v34, v34, v35
	v_mul_f32_e32 v35, 0xbfb8aa3b, v33
	global_load_ushort v120, v231, s[64:65]
	v_mul_f32_e32 v33, 0x3fb8aa3b, v33
	ds_write_b16 v85, v34
	ds_write_b16_d16_hi v86, v34
	ds_write_b16 v85, v32 offset:17408
	ds_write_b16_d16_hi v86, v32 offset:17408
	global_load_ushort v198, v231, s[54:55]
	v_mul_f32_e32 v34, 0x3fb8aa3b, v40
	v_exp_f32_e32 v40, v33
	v_mul_f32_e32 v33, 0x3fb8aa3b, v41
	v_cvt_pk_bf16_f32 v32, v38, v39
	v_exp_f32_e32 v38, v35
	global_load_ushort v214, v231, s[60:61]
	v_add_u32_e32 v232, s70, v228
	v_exp_f32_e32 v35, v33
	v_add_f32_e32 v33, v44, v153
	v_exp_f32_e32 v34, v34
	v_mul_f32_e32 v37, 0xbfb8aa3b, v33
	global_load_ushort v121, v232, s[64:65]
	v_exp_f32_e32 v39, v37
	v_mul_f32_e32 v33, 0x3fb8aa3b, v33
	v_exp_f32_e32 v41, v33
	v_pk_add_f32 v[34:35], v[34:35], 1.0 op_sel_hi:[1,0] neg_lo:[1,0] neg_hi:[1,0]
	s_nop 0
	global_load_ushort v199, v232, s[54:55]
	v_pk_mul_f32 v[34:35], v[34:35], v[38:39]
	v_and_b32_e32 v39, 0xffff0000, v133
	v_lshlrev_b32_e32 v38, 16, v133
	v_pk_mul_f32 v[38:39], v[40:41], v[38:39]
	v_pk_mul_f32 v[40:41], v[36:37], v[34:35] op_sel_hi:[0,1]
	global_load_ushort v215, v232, s[60:61]
	v_add_u32_e32 v233, s72, v228
	v_cvt_pk_bf16_f32 v34, v34, v35
	v_add_f32_e32 v35, v57, v153
	v_cvt_pk_bf16_f32 v33, v38, v39
	v_mul_f32_e32 v37, 0xbfb8aa3b, v35
	v_mul_f32_e32 v35, 0x3fb8aa3b, v35
	global_load_ushort v122, v233, s[64:65]
	ds_write_b16 v87, v33
	ds_write_b16_d16_hi v88, v33
	ds_write_b16 v87, v34 offset:17408
	ds_write_b16_d16_hi v88, v34 offset:17408
	v_cvt_pk_bf16_f32 v33, v40, v41
	global_load_ushort v200, v233, s[54:55]
	v_mul_f32_e32 v34, 0x3fb8aa3b, v45
	v_exp_f32_e32 v38, v37
	v_exp_f32_e32 v40, v35
	v_mul_f32_e32 v35, 0x3fb8aa3b, v46
	global_load_ushort v216, v233, s[60:61]
	v_add_u32_e32 v234, s74, v228
	v_add_f32_e32 v37, v58, v153
	v_exp_f32_e32 v34, v34
	v_exp_f32_e32 v35, v35
	v_mul_f32_e32 v39, 0xbfb8aa3b, v37
	v_exp_f32_e32 v39, v39
	global_load_ushort v123, v234, s[64:65]
	v_mul_f32_e32 v37, 0x3fb8aa3b, v37
	v_exp_f32_e32 v41, v37
	v_pk_add_f32 v[34:35], v[34:35], 1.0 op_sel_hi:[1,0] neg_lo:[1,0] neg_hi:[1,0]
	s_nop 0
	v_pk_mul_f32 v[34:35], v[34:35], v[38:39]
	global_load_ushort v201, v234, s[54:55]
	v_and_b32_e32 v39, 0xffff0000, v134
	v_lshlrev_b32_e32 v38, 16, v134
	v_pk_mul_f32 v[38:39], v[40:41], v[38:39]
	v_pk_mul_f32 v[40:41], v[36:37], v[34:35] op_sel_hi:[0,1]
	v_cvt_pk_bf16_f32 v37, v38, v39
	global_load_ushort v217, v234, s[60:61]
	v_add_u32_e32 v235, s76, v228
	v_cvt_pk_bf16_f32 v34, v34, v35
	ds_write_b16 v89, v37
	ds_write_b16_d16_hi v90, v37
	ds_write_b16 v89, v34 offset:17408
	ds_write_b16_d16_hi v90, v34 offset:17408
	global_load_ushort v115, v235, s[64:65]
	v_add_f32_e32 v35, v59, v153
	v_mul_f32_e32 v37, 0x3fb8aa3b, v47
	v_exp_f32_e32 v38, v37
	v_mul_f32_e32 v37, 0xbfb8aa3b, v35
	global_load_ushort v202, v235, s[54:55]
	v_mul_f32_e32 v35, 0x3fb8aa3b, v35
	v_exp_f32_e32 v42, v35
; template <bool OUT>
; __device__ void phase_hgrn(const Params& p, const bf16_t* Qh, const bf16_t* Vv, const _Float16* Lfb, bf16_t* Of, bf16_t* Ob, float* Sseg, float* Dlog, LAS unsigned char* lds) {
;     ...
;         const float eblast = __expf(blast);
;         unsigned kew[8], vw[8];
; #pragma unroll
;         for (int i = 0; i < 16; i += 2) {
;           float qt[2], kt[2], ke[2];
; #pragma unroll
;           for (int e = 0; e < 2; ++e) {
;             const float bb = offs + cs[i + e];
;             const float k = 1.f - __expf(lf[i + e]);
;             const float ken = k * __expf(-bb);
;             if constexpr (OUT) { qt[e] = bf2f(qr[i + e]) * __expf(bb); kt[e] = ken; }
;             ke[e] = ken * eblast;
;           }
;           if constexpr (OUT) {
;             const unsigned qp = pk2(qt[0], qt[1]), kp = pk2(kt[0], kt[1]);
;             const int s = 16 * tq + i;
;             *(LAS bf16_t*)(lds + QT + (s * 136 + dk) * 2) = (bf16_t)(qp & 0xffffu);
;             *(LAS bf16_t*)(lds + QT + ((s + 1) * 136 + dk) * 2) = (bf16_t)(qp >> 16);
;             *(LAS bf16_t*)(lds + KT + (s * 136 + dk) * 2) = (bf16_t)(kp & 0xffffu);
;             *(LAS bf16_t*)(lds + KT + ((s + 1) * 136 + dk) * 2) = (bf16_t)(kp >> 16);
;           }
;           kew[i >> 1] = pk2(ke[0], ke[1]);
;           vw[i >> 1] = (unsigned)vr[i] | ((unsigned)vr[i + 1] << 16);
;         }
;         *(LAS u32x4*)(lds + KE + (dk * 72 + 16 * tq) * 2) = (u32x4){kew[0], kew[1], kew[2], kew[3]};
;         *(LAS u32x4*)(lds + KE + (dk * 72 + 16 * tq + 8) * 2) = (u32x4){kew[4], kew[5], kew[6], kew[7]};
;         *(LAS u32x4*)(lds + VT + (dk * 72 + 16 * tq) * 2) = (u32x4){vw[0], vw[1], vw[2], vw[3]};
;         *(LAS u32x4*)(lds + VT + (dk * 72 + 16 * tq + 8) * 2) = (u32x4){vw[4], vw[5], vw[6], vw[7]};
;         if (tq == 0) *(LAS float*)(lds + DC + dk * 4) = eblast;
;         dsum += blast;
;       }
;       __syncthreads();
;       if (c + 1 < c_end) {
;         const int cn = c + 1;
;         const int rb = (cn < 4) ? b * 256 + (dir ? 255 - 64 * cn : 64 * cn) : NCTX + b * 8192 + (dir ? 8191 - 64 * (cn - 4) : 64 * (cn - 4));
;         const size_t o0 = (size_t)(rb + sgn * 16 * tq) * DM + h * 128 + dk;
; #pragma unroll
;         for (int i = 0; i < 16; ++i) { const size_t o = o0 + (ptrdiff_t)(sgn * i) * DM; lfr[i] = Lx[o]; if constexpr (OUT) qr[i] = Qh[o]; else qr[i] = 0; vr[i] = Vv[o]; }
	v_mul_f32_e32 v35, 0x3fb8aa3b, v56
	v_exp_f32_e32 v39, v35
	v_add_f32_e32 v35, v60, v153
	global_load_ushort v218, v235, s[60:61]
	v_add_u32_e32 v236, s78, v228
	v_cvt_pk_bf16_f32 v34, v40, v41
	v_exp_f32_e32 v40, v37
	v_mul_f32_e32 v37, 0xbfb8aa3b, v35
	v_exp_f32_e32 v41, v37
	v_mul_f32_e32 v35, 0x3fb8aa3b, v35
	global_load_ushort v116, v236, s[64:65]
	v_exp_f32_e32 v43, v35
	v_pk_add_f32 v[38:39], v[38:39], 1.0 op_sel_hi:[1,0] neg_lo:[1,0] neg_hi:[1,0]
	s_nop 0
	v_pk_mul_f32 v[38:39], v[38:39], v[40:41]
	v_and_b32_e32 v41, 0xffff0000, v135
	global_load_ushort v203, v236, s[54:55]
	v_lshlrev_b32_e32 v40, 16, v135
	v_pk_mul_f32 v[40:41], v[42:43], v[40:41]
	v_pk_mul_f32 v[42:43], v[36:37], v[38:39] op_sel_hi:[0,1]
	v_cvt_pk_bf16_f32 v35, v40, v41
	v_cvt_pk_bf16_f32 v37, v38, v39
	global_load_ushort v219, v236, s[60:61]
	v_add_u32_e32 v237, s80, v228
	ds_write_b16 v91, v35
	ds_write_b16_d16_hi v92, v35
	ds_write_b16 v91, v37 offset:17408
	ds_write_b16_d16_hi v92, v37 offset:17408
	global_load_ushort v125, v237, s[64:65]
	v_add_f32_e32 v37, v141, v153
	v_mul_f32_e32 v39, 0xbfb8aa3b, v37
	v_mul_f32_e32 v37, 0x3fb8aa3b, v37
	v_cvt_pk_bf16_f32 v35, v42, v43
	v_exp_f32_e32 v42, v37
	global_load_ushort v204, v237, s[54:55]
	v_mul_f32_e32 v37, 0x3fb8aa3b, v62
	v_mul_f32_e32 v38, 0x3fb8aa3b, v61
	v_exp_f32_e32 v40, v39
	v_exp_f32_e32 v39, v37
	v_add_f32_e32 v37, v142, v153
	global_load_ushort v220, v237, s[60:61]
	v_add_u32_e32 v230, s82, v228
	v_exp_f32_e32 v38, v38
	v_mul_f32_e32 v41, 0xbfb8aa3b, v37
	v_exp_f32_e32 v41, v41
	v_mul_f32_e32 v37, 0x3fb8aa3b, v37
	v_exp_f32_e32 v43, v37
	global_load_ushort v126, v230, s[64:65]
	v_pk_add_f32 v[38:39], v[38:39], 1.0 op_sel_hi:[1,0] neg_lo:[1,0] neg_hi:[1,0]
	s_nop 0
	v_pk_mul_f32 v[38:39], v[38:39], v[40:41]
	v_and_b32_e32 v41, 0xffff0000, v136
	global_load_ushort v205, v230, s[54:55]
	v_lshlrev_b32_e32 v40, 16, v136
	v_pk_mul_f32 v[40:41], v[42:43], v[40:41]
	v_pk_mul_f32 v[42:43], v[36:37], v[38:39] op_sel_hi:[0,1]
	v_cvt_pk_bf16_f32 v37, v40, v41
	v_cvt_pk_bf16_f32 v38, v38, v39
	global_load_ushort v221, v230, s[60:61]
	v_add_u32_e32 v231, s84, v228
	ds_write_b16 v93, v37
	ds_write_b16_d16_hi v94, v37
	ds_write_b16 v93, v38 offset:17408
	ds_write_b16_d16_hi v94, v38 offset:17408
	v_add_f32_e32 v37, v143, v153
	global_load_ushort v127, v231, s[64:65]
	v_mul_f32_e32 v39, 0x3fb8aa3b, v63
	v_exp_f32_e32 v40, v39
	v_mul_f32_e32 v39, 0xbfb8aa3b, v37
	v_mul_f32_e32 v37, 0x3fb8aa3b, v37
	v_exp_f32_e32 v44, v37
	global_load_ushort v206, v231, s[54:55]
	v_mul_f32_e32 v37, 0x3fb8aa3b, v140
	v_exp_f32_e32 v41, v37
	v_add_f32_e32 v37, v144, v153
	v_cvt_pk_bf16_f32 v38, v42, v43
	v_exp_f32_e32 v42, v39
	global_load_ushort v222, v231, s[60:61]
	v_add_u32_e32 v232, s86, v228
	v_mul_f32_e32 v39, 0xbfb8aa3b, v37
	v_exp_f32_e32 v43, v39
	v_mul_f32_e32 v37, 0x3fb8aa3b, v37
	v_exp_f32_e32 v45, v37
	global_load_ushort v130, v232, s[64:65]
	v_pk_add_f32 v[40:41], v[40:41], 1.0 op_sel_hi:[1,0] neg_lo:[1,0] neg_hi:[1,0]
	s_nop 0
	v_pk_mul_f32 v[40:41], v[40:41], v[42:43]
	v_and_b32_e32 v43, 0xffff0000, v137
	v_lshlrev_b32_e32 v42, 16, v137
	global_load_ushort v207, v232, s[54:55]
	v_pk_mul_f32 v[42:43], v[44:45], v[42:43]
	v_pk_mul_f32 v[44:45], v[36:37], v[40:41] op_sel_hi:[0,1]
	v_cvt_pk_bf16_f32 v37, v42, v43
	v_cvt_pk_bf16_f32 v39, v40, v41
	ds_write_b16 v95, v37
	global_load_ushort v223, v232, s[60:61]
	v_add_u32_e32 v233, s88, v228
	ds_write_b16_d16_hi v96, v37
	ds_write_b16 v95, v39 offset:17408
	ds_write_b16_d16_hi v96, v39 offset:17408
	v_add_f32_e32 v37, v149, v153
	v_mul_f32_e32 v41, 0xbfb8aa3b, v37
	global_load_ushort v131, v233, s[64:65]
	v_mul_f32_e32 v37, 0x3fb8aa3b, v37
	v_cvt_pk_bf16_f32 v39, v44, v45
	v_exp_f32_e32 v44, v37
	v_mul_f32_e32 v37, 0x3fb8aa3b, v146
	v_mul_f32_e32 v40, 0x3fb8aa3b, v145
	global_load_ushort v208, v233, s[54:55]
	v_exp_f32_e32 v42, v41
	v_exp_f32_e32 v41, v37
	v_add_f32_e32 v37, v150, v153
	v_exp_f32_e32 v40, v40
	global_load_ushort v224, v233, s[60:61]
	v_add_u32_e32 v234, s90, v228
	v_mul_f32_e32 v43, 0xbfb8aa3b, v37
	v_exp_f32_e32 v43, v43
	v_mul_f32_e32 v37, 0x3fb8aa3b, v37
	v_exp_f32_e32 v45, v37
	v_pk_add_f32 v[40:41], v[40:41], 1.0 op_sel_hi:[1,0] neg_lo:[1,0] neg_hi:[1,0]
	global_load_ushort v132, v234, s[64:65]
	s_nop 0
	v_pk_mul_f32 v[40:41], v[40:41], v[42:43]
	v_and_b32_e32 v43, 0xffff0000, v138
	v_lshlrev_b32_e32 v42, 16, v138
	v_pk_mul_f32 v[42:43], v[44:45], v[42:43]
	global_load_ushort v209, v234, s[54:55]
	v_pk_mul_f32 v[44:45], v[36:37], v[40:41] op_sel_hi:[0,1]
	v_cvt_pk_bf16_f32 v37, v42, v43
	v_cvt_pk_bf16_f32 v40, v40, v41
	ds_write_b16 v97, v37
	ds_write_b16_d16_hi v98, v37
	global_load_ushort v225, v234, s[60:61]
	v_add_u32_e32 v235, s92, v228
	ds_write_b16 v97, v40 offset:17408
	ds_write_b16_d16_hi v98, v40 offset:17408
	v_add_f32_e32 v37, v151, v153
	v_mul_f32_e32 v41, 0x3fb8aa3b, v147
	v_exp_f32_e32 v42, v41
	global_load_ushort v128, v235, s[64:65]
	v_mul_f32_e32 v41, 0xbfb8aa3b, v37
	v_mul_f32_e32 v37, 0x3fb8aa3b, v37
	v_exp_f32_e32 v46, v37
	v_mul_f32_e32 v37, 0x3fb8aa3b, v148
	global_load_ushort v210, v235, s[54:55]
	v_exp_f32_e32 v43, v37
	v_add_f32_e32 v37, v152, v153
	v_cvt_pk_bf16_f32 v40, v44, v45
	v_exp_f32_e32 v44, v41
	v_mul_f32_e32 v41, 0xbfb8aa3b, v37
	global_load_ushort v226, v235, s[60:61]
	v_add_u32_e32 v236, s94, v228
	v_exp_f32_e32 v45, v41
	v_mul_f32_e32 v37, 0x3fb8aa3b, v37
	v_exp_f32_e32 v47, v37
	v_pk_add_f32 v[42:43], v[42:43], 1.0 op_sel_hi:[1,0] neg_lo:[1,0] neg_hi:[1,0]
	s_nop 0
	global_load_ushort v129, v236, s[64:65]
	v_pk_mul_f32 v[42:43], v[42:43], v[44:45]
	v_and_b32_e32 v45, 0xffff0000, v139
	v_lshlrev_b32_e32 v44, 16, v139
	v_pk_mul_f32 v[44:45], v[46:47], v[44:45]
	v_pk_mul_f32 v[46:47], v[36:37], v[42:43] op_sel_hi:[0,1]
	global_load_ushort v211, v236, s[54:55]
	v_cvt_pk_bf16_f32 v37, v44, v45
	v_cvt_pk_bf16_f32 v41, v42, v43
	ds_write_b16 v99, v37
	ds_write_b16_d16_hi v100, v37
	ds_write_b16 v99, v41 offset:17408
	global_load_ushort v227, v236, s[60:61]
	ds_write_b16_d16_hi v100, v41 offset:17408
	v_cvt_pk_bf16_f32 v41, v46, v47
	ds_write_b128 v101, v[32:35] offset:34816
	ds_write_b128 v101, v[38:41] offset:34832
	ds_write_b128 v101, v[48:51] offset:53248
	ds_write_b128 v101, v[52:55] offset:53264
	s_and_saveexec_b64 s[0:1], s[6:7]
	v_add_u32_e32 v32, 0, v79
	v_add_u32_e32 v32, 0x1c400, v32
	ds_write_b32 v32, v36
	s_or_b64 exec, exec, s[0:1]
	s_add_i32 s4, s34, 1
	s_cmp_ge_u32 s4, s31
	s_waitcnt lgkmcnt(0)
	s_barrier

; __device__ __forceinline__ unsigned pk2(float lo, float hi) { f32x2 v = {lo, hi}; return __builtin_bit_cast(unsigned, __builtin_convertvector(v, bf16v2)); }
; #define LAS __attribute__((address_space(3)))
; template <bool OUT>
; __device__ void phase_hgrn(const Params& p, const bf16_t* Qh, const bf16_t* Vv, const _Float16* Lfb, bf16_t* Of, bf16_t* Ob, float* Sseg, float* Dlog, LAS unsigned char* lds) {
;     ...
; #pragma unroll
;         for (int ks = 0; ks < 8; ++ks) {
;           const bf16x8 sa = *(const LAS bf16x8*)(lds + ST + ((32 * dvb + r) * 136 + 16 * ks + 8 * hh) * 2);
;           const bf16x8 qb = *(const LAS bf16x8*)(lds + QT + ((32 * tb + r) * 136 + 16 * ks + 8 * hh) * 2);
;           o = __builtin_amdgcn_mfma_f32_32x32x16_bf16(sa, qb, o, 0, 0, 0);
;         }
;         if (c >= 4) {
;           const int row = rbase + sgn * (32 * tb + r);
;           bf16_t* op = (dir ? Ob + (size_t)(row - NCTX) * DM : Of + (size_t)row * DM) + h * 128 + 32 * dvb + 4 * hh;
; #pragma unroll
;           for (int g = 0; g < 4; ++g) {
;             u32x2 ov; ov.x = pk2(o[4 * g], o[4 * g + 1]); ov.y = pk2(o[4 * g + 2], o[4 * g + 3]);
;             *(u32x2*)(op + 8 * g) = ov;
;           }
;         }
.LBB0_2306:
	s_or_b64 exec, exec, s[0:1]
	ds_read_b128 v[140:143], v110
	ds_read_b128 v[144:147], v111
	ds_read_b128 v[148:151], v110 offset:32
	ds_read_b128 v[152:155], v111 offset:32
	v_mfma_f32_32x32x16_bf16 v[16:31], v[60:63], v[56:59], v[16:31]
	s_cmp_lt_u32 s34, 4
	s_waitcnt lgkmcnt(2)
	v_mfma_f32_32x32x16_bf16 v[32:47], v[140:143], v[144:147], v[32:47]
	s_waitcnt lgkmcnt(0)
	v_mfma_f32_32x32x16_bf16 v[32:47], v[148:151], v[152:155], v[32:47]
	ds_read_b128 v[140:143], v110 offset:64
	ds_read_b128 v[144:147], v111 offset:64
	ds_read_b128 v[148:151], v110 offset:96
	ds_read_b128 v[152:155], v111 offset:96
	s_waitcnt lgkmcnt(2)
	v_mfma_f32_32x32x16_bf16 v[32:47], v[140:143], v[144:147], v[32:47]
	s_waitcnt lgkmcnt(0)
	v_mfma_f32_32x32x16_bf16 v[32:47], v[148:151], v[152:155], v[32:47]
	ds_read_b128 v[140:143], v110 offset:128
	ds_read_b128 v[144:147], v111 offset:128
	ds_read_b128 v[148:151], v110 offset:160
	ds_read_b128 v[152:155], v111 offset:160
	s_waitcnt lgkmcnt(2)
	v_mfma_f32_32x32x16_bf16 v[32:47], v[140:143], v[144:147], v[32:47]
	s_waitcnt lgkmcnt(0)
	v_mfma_f32_32x32x16_bf16 v[32:47], v[148:151], v[152:155], v[32:47]
	ds_read_b128 v[140:143], v110 offset:192
	ds_read_b128 v[144:147], v111 offset:192
	ds_read_b128 v[148:151], v110 offset:224
	ds_read_b128 v[152:155], v111 offset:224
	s_waitcnt lgkmcnt(2)
	v_mfma_f32_32x32x16_bf16 v[32:47], v[140:143], v[144:147], v[32:47]
	s_waitcnt lgkmcnt(0)
	v_mfma_f32_32x32x16_bf16 v[32:47], v[148:151], v[152:155], v[32:47]
	s_waitcnt vmcnt(0)
	v_lshl_or_b32 v75, v197, 16, v196
	v_lshl_or_b32 v133, v199, 16, v198
	v_lshl_or_b32 v134, v201, 16, v200
	v_lshl_or_b32 v135, v203, 16, v202
	v_lshl_or_b32 v136, v205, 16, v204
	v_lshl_or_b32 v137, v207, 16, v206
	v_lshl_or_b32 v138, v209, 16, v208
	v_lshl_or_b32 v139, v211, 16, v210
	v_lshl_or_b32 v48, v213, 16, v212
	v_lshl_or_b32 v49, v215, 16, v214
	v_lshl_or_b32 v50, v217, 16, v216
	v_lshl_or_b32 v51, v219, 16, v218
	v_lshl_or_b32 v52, v221, 16, v220
	v_lshl_or_b32 v53, v223, 16, v222
	v_lshl_or_b32 v54, v225, 16, v224
	v_lshl_or_b32 v55, v227, 16, v226
	s_cbranch_scc1 .LBB0_2287
	v_add_u32_e32 v56, s3, v124
	v_add_u32_e32 v57, 0xfffffc00, v56
	v_cndmask_b32_e64 v56, v57, v56, s[50:51]
	v_ashrrev_i32_e32 v57, 31, v56
	v_lshlrev_b64 v[56:57], 11, v[56:57]
	v_lshl_add_u64 v[56:57], v[76:77], 0, v[56:57]
	s_nop 4
	v_cvt_pk_bf16_f32 v32, v32, v33
	v_cvt_pk_bf16_f32 v33, v34, v35
	global_store_dwordx2 v[56:57], v[32:33], off
	v_cvt_pk_bf16_f32 v32, v36, v37
	v_cvt_pk_bf16_f32 v33, v38, v39
	global_store_dwordx2 v[56:57], v[32:33], off offset:16
	v_cvt_pk_bf16_f32 v32, v40, v41
	v_cvt_pk_bf16_f32 v33, v42, v43
	global_store_dwordx2 v[56:57], v[32:33], off offset:32
	v_cvt_pk_bf16_f32 v32, v44, v45
	v_cvt_pk_bf16_f32 v33, v46, v47
	global_store_dwordx2 v[56:57], v[32:33], off offset:48
	s_branch .LBB0_2287
